# SSD scan: waves 2,3 dt gathers made uniform-address (unused values); on top of attention PV-phase prefetch
# speedup vs baseline: 1.0113x; 1.0065x over previous
; __device__ __forceinline__ void ssd_scan_item(CParams& p, int j2, int b, int dir, int h, int pq, bf16_t* smem) {
;     const int tid = tid_(), lane = tid & 63, wave = tid >> 6, l16 = lane & 15, quad = lane >> 4;
;     const int g = h >> 3;
;     bf16_t* sX = smem;
;     bf16_t* sH = sX + 16 * SST;
;     float* seacs = (float*)(sH + 16 * SST);
;     float* sw = seacs + 128;
;     float* sdec = sw + 128;
;     const bf16_t* XT = (const bf16_t*)(p.ws + WS_XT) + (size_t)(h * 64 + pq * 16 + (tid >> 4)) * MT + (tid & 15) * 8;
;     const bf16_t* Cn = (const bf16_t*)(p.ws + WS_CN) + ((size_t)(wave * 2) * 16 + g * 4) * 512 + lane * 8;
;     const bf16_t* BT = (const bf16_t*)(p.ws + WS_BT) + (size_t)(g * 8 + wave * 2) * (MT / 32) * 512 + lane * 8;
;     const float* DT = (const float*)(p.ws + WS_DT) + dir * 32 + h;
;     bf16_t* Y = (bf16_t*)(p.ws + (dir ? WS_YB : WS_YF)) + frag_off(wave * 32 + l16, h * 64 + pq * 16 + quad * 4, 2048);
;     const float a = -expf(p.ssm_a_log[(j2 * 2 + dir) * 32 + h]);
;     f32x4 st[2];
;     st[0] = (f32x4){0.f, 0.f, 0.f, 0.f}; st[1] = (f32x4){0.f, 0.f, 0.f, 0.f};
;     SsdPre S0, S1;
;     auto load_small = [&](SsdPre& S, int r) __attribute__((always_inline)) {
;         S.xq = *(const u32x4*)(XT + r);
;         S.dt0 = DT[(size_t)(r + lane) * 64]; S.dt1 = DT[(size_t)(r + 64 + lane) * 64];
;     };
;     auto load_cf = [&](SsdPre& S, int r) __attribute__((always_inline)) {
; #pragma unroll
;         for (int i = 0; i < 2; ++i)
; #pragma unroll
;             for (int ks = 0; ks < 4; ++ks) S.cf[i][ks] = *(const u32x4*)(Cn + ((size_t)((r >> 4) + i) * 16 + ks) * 512);
;     };
;     auto load_yold = [&](SsdPre& S, int r) __attribute__((always_inline)) {
; #pragma unroll
;         for (int i = 0; i < 2; ++i) S.yold[i] = dir == 0 ? *(const u32x2*)(Y + (size_t)((r >> 4) + i) * (64 * 512)) : (u32x2){0u, 0u};
;     };
;     auto load_bt = [&](SsdPre& S, int r) __attribute__((always_inline)) {
; #pragma unroll
;         for (int nt = 0; nt < 2; ++nt)
; #pragma unroll
;             for (int ks = 0; ks < 4; ++ks) S.bt[nt][ks] = *(const u32x4*)(BT + ((size_t)nt * (MT / 32) + (r >> 5) + ks) * 512);
;     };
;     {
;         const int r0 = ssd_row0(b, dir, 0), r1 = ssd_row0(b, dir, 1);
;         load_small(S0, r0); load_cf(S0, r0); load_yold(S0, r0); load_bt(S0, r0);
.LBB0_460:
	s_waitcnt vmcnt(30)
	v_mul_f32_e32 v107, 0x3fb8aa3b, v106
	v_rndne_f32_e32 v112, v107
	v_sub_f32_e32 v113, v107, v112
	v_fma_f32 v107, v106, s28, -v107
	v_fmac_f32_e32 v107, 0x32a5705f, v106
	v_add_f32_e32 v107, v113, v107
	v_cvt_i32_f32_e32 v112, v112
	v_exp_f32_e32 v107, v107
	v_mul_lo_u32 v104, v104, s91
	v_cmp_ngt_f32_e32 vcc, s90, v106
	v_add3_u32 v164, 0, v104, v164
	v_ldexp_f32 v107, v107, v112
	v_mul_u32_u24_e32 v104, 0x88, v103
	v_cndmask_b32_e32 v107, 0, v107, vcc
	v_cmp_nlt_f32_e32 vcc, s89, v106
	v_lshl_add_u32 v104, v104, 1, 0
	v_lshlrev_b32_e32 v106, 6, v102
	v_lshlrev_b32_e32 v105, 1, v105
	v_cmp_gt_i32_e64 s[44:45], 2, v102
	v_lshlrev_b32_e32 v102, 7, v102
	v_lshlrev_b32_e32 v103, 2, v103
	v_cndmask_b32_e32 v163, v208, v107, vcc
	s_lshl_b32 s17, s24, 13
	v_add3_u32 v169, v104, v106, v105
	v_lshl_add_u32 v170, v101, 4, v104
	v_add3_u32 v171, 0, v102, v103
	v_lshl_add_u32 v172, v101, 5, 0
	v_cmp_eq_u32_e64 s[46:47], 63, v160
	v_cmp_gt_u32_e64 s[48:49], 62, v160
	v_cmp_gt_u32_e64 s[50:51], 60, v160
	v_cmp_gt_u32_e64 s[52:53], 56, v160
	v_cmp_gt_u32_e64 s[54:55], 48, v160
	v_cmp_gt_u32_e64 s[56:57], 32, v160
	s_mov_b32 s77, 0
	v_cmp_eq_u32_e64 s[58:59], 0, v160
	v_cmp_gt_u32_e64 s[60:61], 2, v160
	v_cmp_gt_u32_e64 s[62:63], 4, v160
	v_cmp_gt_u32_e64 s[64:65], 8, v160
	v_cmp_gt_u32_e64 s[66:67], 16, v160
	v_cmp_lt_u32_e64 s[68:69], 63, v100
	v_lshl_add_u32 v174, v160, 2, 0
	v_cndmask_b32_e64 v160, 0, v160, s[44:45]
	s_movk_i32 s19, 0x41
	v_mov_b32_e32 v100, s18
	v_mov_b32_e32 v137, v136
	v_mov_b32_e32 v138, v136
	v_mov_b32_e32 v139, v136
	v_mov_b32_e32 v140, v136
	v_mov_b32_e32 v141, v136
	v_mov_b32_e32 v142, v136
	v_mov_b32_e32 v143, v136
	s_branch .LBB0_463
